# attention: diagonal mask via one subtraction + inline-constant compares into three rotating mask registers; K-fragment and staging LDS base addresses hoisted out of the tile loop
# speedup vs baseline: 1.0083x; 1.0011x over previous
.LBB0_517:
	s_or_b64 exec, exec, s[0:1]
	s_add_i32 s62, 0, 0x22820
	v_mov_b32_e32 v8, s62
	s_waitcnt lgkmcnt(0)
	s_barrier
	ds_read_b32 v8, v8
	s_movk_i32 s0, 0x7ff
	s_mov_b32 s9, 0
	s_waitcnt lgkmcnt(0)
	s_barrier
	v_cmp_lt_i32_e32 vcc, s0, v8
	v_readfirstlane_b32 s60, v8
	s_cbranch_vccnz .LBB0_565
	v_add_f32_e32 v6, v6, v7
	s_mov_b32 s0, 0x3fb8aa3b
	v_mul_f32_e32 v7, 0x3fb8aa3b, v6
	v_fma_f32 v8, v6, s0, -v7
	v_rndne_f32_e32 v9, v7
	v_fmac_f32_e32 v8, 0x32a5705f, v6
	v_sub_f32_e32 v7, v7, v9
	v_add_f32_e32 v7, v7, v8
	v_exp_f32_e32 v7, v7
	v_cvt_i32_f32_e32 v8, v9
	v_add_f32_e32 v4, v4, v5
	s_mov_b32 s1, 0xc2ce8ed0
	v_cmp_ngt_f32_e32 vcc, s1, v6
	v_ldexp_f32 v5, v7, v8
	v_mul_f32_e32 v7, 0x3fb8aa3b, v4
	v_fma_f32 v8, v4, s0, -v7
	v_rndne_f32_e32 v9, v7
	v_fmac_f32_e32 v8, 0x32a5705f, v4
	v_sub_f32_e32 v7, v7, v9
	v_add_f32_e32 v7, v7, v8
	v_exp_f32_e32 v7, v7
	v_cvt_i32_f32_e32 v8, v9
	s_mov_b32 s4, 0x42b17218
	v_cndmask_b32_e32 v5, 0, v5, vcc
	v_mov_b32_e32 v9, 0x7f800000
	v_cmp_nlt_f32_e32 vcc, s4, v6
	v_ldexp_f32 v6, v7, v8
	s_waitcnt vmcnt(0)
	v_add_f32_e32 v3, v3, v3
	v_cndmask_b32_e32 v5, v9, v5, vcc
	v_cmp_ngt_f32_e32 vcc, s1, v4
	s_mov_b32 s71, 0xf800000
	s_add_u32 s63, s50, 0x8000000
	v_cndmask_b32_e32 v6, 0, v6, vcc
	v_cmp_nlt_f32_e32 vcc, s4, v4
	s_addc_u32 s64, s51, 0
	s_add_u32 s65, s50, 0xc000000
	v_cndmask_b32_e32 v4, v9, v6, vcc
	v_sub_f32_e32 v4, v5, v4
	v_mul_f32_e32 v5, 0x4f800000, v3
	v_cmp_gt_f32_e32 vcc, s71, v3
	v_lshlrev_b32_e32 v6, 3, v1
	v_add_f32_e32 v169, 0x3e4ccccd, v4
	v_cndmask_b32_e32 v3, v3, v5, vcc
	v_sqrt_f32_e32 v5, v3
	v_lshlrev_b32_e32 v4, 1, v1
	v_and_b32_e32 v6, 24, v6
	v_and_or_b32 v9, v4, 32, v6
	v_add_u32_e32 v4, -1, v5
	v_fma_f32 v6, -v4, v5, v3
	v_cmp_ge_f32_e64 s[0:1], 0, v6
	v_add_u32_e32 v6, 1, v5
	s_addc_u32 s70, s51, 0
	v_cndmask_b32_e64 v4, v5, v4, s[0:1]
	v_fma_f32 v5, -v6, v5, v3
	v_cmp_lt_f32_e64 s[0:1], 0, v5
	s_lshr_b32 s4, s10, 6
	s_bfe_u32 s5, s10, 0x10008
	v_cndmask_b32_e64 v4, v4, v6, s[0:1]
	v_lshrrev_b32_e32 v199, 4, v1
	v_mul_f32_e32 v5, 0x37800000, v4
	s_lshl_b32 s4, s4, 2
	v_cndmask_b32_e32 v4, v4, v5, vcc
	v_mov_b32_e32 v5, s67
	s_add_i32 s67, s4, 0
	s_movk_i32 s4, 0x110
	v_add_u32_e32 v10, 32, v199
	s_lshl_b32 s12, s5, 7
	v_mad_u32_u24 v202, v199, s4, 0
	v_mul_u32_u24_e32 v11, 48, v10
	s_movk_i32 s11, 0x2200
	s_add_i32 s12, s12, 0
	v_or_b32_e32 v7, v166, v174
	v_mov_b32_e32 v200, 0x260
	v_lshlrev_b32_e32 v6, 3, v2
	v_mad_u32_u24 v204, v199, 48, v202
	v_add3_u32 v12, v202, v11, s11
	s_movk_i32 s11, 0x140
	v_lshlrev_b32_e32 v205, 4, v2
	v_mov_b32_e32 v2, s12
	s_bfe_u32 s8, s10, 0x20006
	s_lshl_b32 s98, s5, 1
	s_xor_b32 s8, s8, s98
	v_cmp_class_f32_e32 vcc, v3, v200
	v_mul_i32_i24_e32 v7, 0x140, v7
	v_mad_u32_u24 v206, v178, s4, v2
	v_add_u32_e32 v208, 0x2800, v204
	v_mad_u32_u24 v209, v199, s11, 0
	s_movk_i32 s4, 0xffd0
	v_cndmask_b32_e32 v3, v4, v3, vcc
	v_add3_u32 v207, 0, v9, v7
	v_mad_i32_i24 v2, v10, s4, v208
	v_mad_i32_i24 v7, v199, s4, v209
	s_lshl_b32 s4, s8, 14
	v_mul_f32_e32 v201, 0x3f828f5c, v3
	v_mov_b32_e32 v3, 0
	s_add_i32 s4, s4, 0
	v_mov_b32_e32 v4, s66
	s_lshl_b32 s66, s8, 5
	s_lshl_b32 s14, s5, 6
	v_lshlrev_b32_e32 v8, 3, v167
	s_add_i32 s67, s67, 0x22800
	v_lshlrev_b32_e32 v203, 4, v167
	s_add_i32 s4, s4, 0x12800
	s_and_b32 s8, 0x100, s10
	v_mov_b32_e32 v167, v3
	s_cmp_eq_u32 s5, 0
	v_add_u32_e32 v170, v206, v205
	v_add_u32_e32 v171, v209, v203
	v_lshlrev_b64 v[4:5], 1, v[166:167]
	s_cselect_b64 s[10:11], -1, 0
	s_cmp_lg_u32 s8, 0
	v_lshl_add_u32 v211, v142, 2, s4
	v_lshl_add_u64 v[10:11], s[50:51], 0, v[4:5]
	s_mov_b64 s[4:5], 0x10000000
	v_lshl_add_u64 v[176:177], s[42:43], 0, v[4:5]
	v_sub_u32_e32 v4, v166, v178
	s_mov_b32 s16, 2.0
	s_mov_b32 s18, 0x41000000
	s_mov_b32 s20, 0x41200000
	s_mov_b32 s22, 0x41800000
	s_mov_b32 s24, 0x41900000
	s_mov_b32 s36, 0x41c00000
	s_mov_b32 s54, 0x41d00000
	v_or_b32_e32 v198, 0x780, v178
	v_cmp_eq_u32_e64 s[0:1], 0, v142
	v_add_u32_e32 v210, 0xd800, v207
	s_cselect_b64 s[12:13], -1, 0
	v_mov_b32_e32 v172, v169
	v_mov_b32_e32 v173, v169
	v_lshl_add_u64 v[174:175], v[10:11], 0, s[4:5]
	v_subrev_u32_e32 v167, s66, v4
	s_lshl_b32 s14, s14, 1
	s_mov_b32 s15, s9
	v_lshlrev_b32_e32 v178, 1, v6
	s_mov_b32 s72, 0x42fc0000
	v_lshlrev_b32_e32 v180, 1, v8
	s_mov_b32 s73, 0x10000
	s_mov_b32 s17, 0x40400000
	s_add_i32 s74, 0, 0x22810
	s_mov_b32 s75, 0x425c0000
	s_mov_b32 s19, 0x41100000
	s_mov_b32 s21, 0x41300000
	s_mov_b32 s23, 0x41880000
	s_mov_b32 s25, 0x41980000
	s_mov_b32 s37, 0x41c80000
	s_mov_b32 s55, 0x41d80000
	v_add_u32_e32 v212, v7, v203
	v_add_u32_e32 v213, v2, v203
	v_mov_b32_e32 v214, 0x3727c5ac
	s_mov_b32 s76, 0x3f4ccccd
	s_movk_i32 s77, 0x800
	v_mov_b32_e32 v215, 0x42800000
	v_add_u32_e32 v216, v12, v203
	v_mov_b32_e32 v217, 0xff800000
	s_branch .LBB0_520

.LBB0_532:
	s_add_i32 s60, s84, s83
	s_add_i32 s56, s60, 0x7c0
	s_cmp_gt_i32 s56, s79
	s_cbranch_scc1 .LBB0_541
	ds_read_b128 v[4:7], v170
	ds_read_b128 v[8:11], v170 offset:32
	v_add3_u32 v2, s84, v220, 64
	v_cvt_f32_i32_e32 v2, v2
	s_andn2_b64 vcc, exec, s[58:59]
	v_fma_f32 v2, v190, v2, -v185
	v_fma_f32 v82, 0, v190, v2
	v_add_f32_e32 v83, v190, v2
	v_fma_f32 v84, v190, s16, v2
	v_fma_f32 v85, v191, s17, v2
	v_fma_f32 v86, v190, s18, v2
	v_fma_f32 v87, v191, s19, v2
	v_fma_f32 v88, v190, s20, v2
	v_fma_f32 v89, v191, s21, v2
	v_fma_f32 v90, v190, s22, v2
	v_fma_f32 v91, v191, s23, v2
	v_fma_f32 v92, v190, s24, v2
	v_fma_f32 v93, v191, s25, v2
	v_fma_f32 v94, v190, s36, v2
	v_fma_f32 v95, v191, s37, v2
	v_fma_f32 v96, v190, s54, v2
	v_fma_f32 v97, v191, s55, v2
	v_add_f32_e32 v2, v219, v2
	v_fma_f32 v98, 0, v190, v2
	s_waitcnt lgkmcnt(1)
	v_mfma_f32_32x32x16_bf16 v[82:97], v[4:7], v[114:117], v[82:97]
	v_add_f32_e32 v99, v190, v2
	v_fma_f32 v100, v190, s16, v2
	v_fma_f32 v101, v191, s17, v2
	v_fma_f32 v102, v190, s18, v2
	v_fma_f32 v103, v191, s19, v2
	v_fma_f32 v104, v190, s20, v2
	v_fma_f32 v105, v191, s21, v2
	v_fma_f32 v106, v190, s22, v2
	v_fma_f32 v107, v191, s23, v2
	v_fma_f32 v108, v190, s24, v2
	v_fma_f32 v109, v191, s25, v2
	v_fma_f32 v110, v190, s36, v2
	v_fma_f32 v111, v191, s37, v2
	s_waitcnt lgkmcnt(0)
	v_mfma_f32_32x32x16_bf16 v[82:97], v[8:11], v[118:121], v[82:97]
	ds_read_b128 v[4:7], v170 offset:64
	ds_read_b128 v[8:11], v170 offset:96
	v_fma_f32 v112, v190, s54, v2
	v_fma_f32 v113, v191, s55, v2
	s_waitcnt lgkmcnt(1)
	v_mfma_f32_32x32x16_bf16 v[82:97], v[4:7], v[122:125], v[82:97]
	ds_read_b128 v[4:7], v170 offset:8704
	ds_read_b128 v[12:15], v170 offset:8736
	s_waitcnt lgkmcnt(1)
	v_mfma_f32_32x32x16_bf16 v[98:113], v[4:7], v[114:117], v[98:113]
	s_waitcnt lgkmcnt(0)
	v_mfma_f32_32x32x16_bf16 v[98:113], v[12:15], v[118:121], v[98:113]
	v_mfma_f32_32x32x16_bf16 v[82:97], v[8:11], v[126:129], v[82:97]
	ds_read_b128 v[4:7], v170 offset:8768
	ds_read_b128 v[224:227], v170 offset:8800
	ds_read_b64_tr_b16 v[12:13], v207 offset:17408
	ds_read_b64_tr_b16 v[14:15], v207 offset:19968
	ds_read_b64_tr_b16 v[8:9], v207 offset:17472
	ds_read_b64_tr_b16 v[10:11], v207 offset:20032
	s_waitcnt lgkmcnt(5)
	v_mfma_f32_32x32x16_bf16 v[98:113], v[4:7], v[122:125], v[98:113]
	ds_read_b64_tr_b16 v[162:163], v207 offset:17536
	ds_read_b64_tr_b16 v[164:165], v207 offset:20096
	ds_read_b64_tr_b16 v[4:5], v207 offset:17600
	ds_read_b64_tr_b16 v[6:7], v207 offset:20160
	s_waitcnt lgkmcnt(8)
	v_mfma_f32_32x32x16_bf16 v[98:113], v[224:227], v[126:129], v[98:113]
	s_cbranch_vccz .Lmy_maskA

.LBB0_541:
	s_add_i32 s61, s85, 1
	s_cmp_lt_i32 s61, s8
	s_cselect_b64 s[56:57], -1, 0
	s_cmp_ge_i32 s61, s8
	s_cbranch_scc1 .LBB0_543
	s_waitcnt vmcnt(3)
	ds_write_b128 v212, v[130:133] offset:37888
	s_waitcnt vmcnt(1)
	ds_write_b128 v213, v[142:145] offset:37888
	s_waitcnt vmcnt(1)
	ds_write_b128 v171, v[138:141] offset:55296
	v_add_u32_e32 v2, v208, v203
	s_waitcnt vmcnt(0)
	ds_write_b128 v2, v[150:153] offset:55296

.LBB0_549:
	ds_read_b128 v[4:7], v170 offset:37888
	ds_read_b128 v[8:11], v170 offset:37920
	v_add_u32_e32 v2, s84, v220
	v_cvt_f32_i32_e32 v2, v2
	s_andn2_b64 vcc, exec, s[58:59]
	v_fma_f32 v2, v190, v2, -v185
	v_fma_f32 v82, 0, v190, v2
	v_add_f32_e32 v83, v190, v2
	v_fma_f32 v84, v190, s16, v2
	v_fma_f32 v85, v191, s17, v2
	v_fma_f32 v86, v190, s18, v2
	v_fma_f32 v87, v191, s19, v2
	v_fma_f32 v88, v190, s20, v2
	v_fma_f32 v89, v191, s21, v2
	v_fma_f32 v90, v190, s22, v2
	v_fma_f32 v91, v191, s23, v2
	v_fma_f32 v92, v190, s24, v2
	v_fma_f32 v93, v191, s25, v2
	v_fma_f32 v94, v190, s36, v2
	v_fma_f32 v95, v191, s37, v2
	v_fma_f32 v96, v190, s54, v2
	v_fma_f32 v97, v191, s55, v2
	v_add_f32_e32 v2, v219, v2
	v_fma_f32 v98, 0, v190, v2
	s_waitcnt lgkmcnt(1)
	v_mfma_f32_32x32x16_bf16 v[82:97], v[4:7], v[114:117], v[82:97]
	v_add_f32_e32 v99, v190, v2
	v_fma_f32 v100, v190, s16, v2
	v_fma_f32 v101, v191, s17, v2
	v_fma_f32 v102, v190, s18, v2
	v_fma_f32 v103, v191, s19, v2
	v_fma_f32 v104, v190, s20, v2
	v_fma_f32 v105, v191, s21, v2
	v_fma_f32 v106, v190, s22, v2
	v_fma_f32 v107, v191, s23, v2
	v_fma_f32 v108, v190, s24, v2
	v_fma_f32 v109, v191, s25, v2
	v_fma_f32 v110, v190, s36, v2
	v_fma_f32 v111, v191, s37, v2
	s_waitcnt lgkmcnt(0)
	v_mfma_f32_32x32x16_bf16 v[82:97], v[8:11], v[118:121], v[82:97]
	ds_read_b128 v[4:7], v170 offset:37952
	ds_read_b128 v[8:11], v170 offset:37984
	v_fma_f32 v112, v190, s54, v2
	v_fma_f32 v113, v191, s55, v2
	s_waitcnt lgkmcnt(1)
	v_mfma_f32_32x32x16_bf16 v[82:97], v[4:7], v[122:125], v[82:97]
	ds_read_b128 v[4:7], v170 offset:46592
	ds_read_b128 v[12:15], v170 offset:46624
	s_waitcnt lgkmcnt(1)
	v_mfma_f32_32x32x16_bf16 v[98:113], v[4:7], v[114:117], v[98:113]
	s_waitcnt lgkmcnt(0)
	v_mfma_f32_32x32x16_bf16 v[98:113], v[12:15], v[118:121], v[98:113]
	ds_read_b128 v[4:7], v170 offset:46656
	ds_read_b128 v[224:227], v170 offset:46688
	ds_read_b64_tr_b16 v[162:163], v210 offset:0
	ds_read_b64_tr_b16 v[164:165], v210 offset:2560
	ds_read_b64_tr_b16 v[12:13], v210 offset:64
	ds_read_b64_tr_b16 v[14:15], v210 offset:2624
	s_waitcnt lgkmcnt(5)
	v_mfma_f32_32x32x16_bf16 v[98:113], v[4:7], v[122:125], v[98:113]
	v_mfma_f32_32x32x16_bf16 v[82:97], v[8:11], v[126:129], v[82:97]
	ds_read_b64_tr_b16 v[8:9], v210 offset:128
	ds_read_b64_tr_b16 v[10:11], v210 offset:2688
	ds_read_b64_tr_b16 v[4:5], v210 offset:192
	ds_read_b64_tr_b16 v[6:7], v210 offset:2752
	s_waitcnt lgkmcnt(8)
	v_mfma_f32_32x32x16_bf16 v[98:113], v[224:227], v[126:129], v[98:113]
	s_cbranch_vccz .Lmy_maskB

.Lmy_maskA:
	v_add_u32_e32 v2, s84, v222
	v_sub_u32_e32 v16, v184, v2
	v_subrev_u32_e32 v16, 0x7c0, v16
	v_cmp_le_i32_e64 vcc, 0, v16
	v_cmp_le_i32_e64 s[98:99], 1, v16
	v_cmp_le_i32_e64 s[96:97], 2, v16
	v_cndmask_b32_e64 v82, v217, v82, vcc
	v_cndmask_b32_e64 v83, v217, v83, s[98:99]
	v_cndmask_b32_e64 v84, v217, v84, s[96:97]
	v_cmp_le_i32_e64 vcc, 3, v16
	v_cmp_le_i32_e64 s[98:99], 8, v16
	v_cmp_le_i32_e64 s[96:97], 9, v16
	v_cndmask_b32_e64 v85, v217, v85, vcc
	v_cndmask_b32_e64 v86, v217, v86, s[98:99]
	v_cndmask_b32_e64 v87, v217, v87, s[96:97]
	v_cmp_le_i32_e64 vcc, 10, v16
	v_cmp_le_i32_e64 s[98:99], 11, v16
	v_cmp_le_i32_e64 s[96:97], 16, v16
	v_cndmask_b32_e64 v88, v217, v88, vcc
	v_cndmask_b32_e64 v89, v217, v89, s[98:99]
	v_cndmask_b32_e64 v90, v217, v90, s[96:97]
	v_cmp_le_i32_e64 vcc, 17, v16
	v_cmp_le_i32_e64 s[98:99], 18, v16
	v_cmp_le_i32_e64 s[96:97], 19, v16
	v_cndmask_b32_e64 v91, v217, v91, vcc
	v_cndmask_b32_e64 v92, v217, v92, s[98:99]
	v_cndmask_b32_e64 v93, v217, v93, s[96:97]
	v_cmp_le_i32_e64 vcc, 24, v16
	v_cmp_le_i32_e64 s[98:99], 25, v16
	v_cmp_le_i32_e64 s[96:97], 26, v16
	v_cndmask_b32_e64 v94, v217, v94, vcc
	v_cndmask_b32_e64 v95, v217, v95, s[98:99]
	v_cndmask_b32_e64 v96, v217, v96, s[96:97]
	v_cmp_le_i32_e64 vcc, 27, v16
	v_cmp_le_i32_e64 s[98:99], 32, v16
	v_cmp_le_i32_e64 s[96:97], 33, v16
	v_cndmask_b32_e64 v97, v217, v97, vcc
	v_cndmask_b32_e64 v98, v217, v98, s[98:99]
	v_cndmask_b32_e64 v99, v217, v99, s[96:97]
	v_cmp_le_i32_e64 vcc, 34, v16
	v_cmp_le_i32_e64 s[98:99], 35, v16
	v_cmp_le_i32_e64 s[96:97], 40, v16
	v_cndmask_b32_e64 v100, v217, v100, vcc
	v_cndmask_b32_e64 v101, v217, v101, s[98:99]
	v_cndmask_b32_e64 v102, v217, v102, s[96:97]
	v_cmp_le_i32_e64 vcc, 41, v16
	v_cmp_le_i32_e64 s[98:99], 42, v16
	v_cmp_le_i32_e64 s[96:97], 43, v16
	v_cndmask_b32_e64 v103, v217, v103, vcc
	v_cndmask_b32_e64 v104, v217, v104, s[98:99]
	v_cndmask_b32_e64 v105, v217, v105, s[96:97]
	v_cmp_le_i32_e64 vcc, 48, v16
	v_cmp_le_i32_e64 s[98:99], 49, v16
	v_cmp_le_i32_e64 s[96:97], 50, v16
	v_cndmask_b32_e64 v106, v217, v106, vcc
	v_cndmask_b32_e64 v107, v217, v107, s[98:99]
	v_cndmask_b32_e64 v108, v217, v108, s[96:97]
	v_cmp_le_i32_e64 vcc, 51, v16
	v_cmp_le_i32_e64 s[98:99], 56, v16
	v_cmp_le_i32_e64 s[96:97], 57, v16
	v_cndmask_b32_e64 v109, v217, v109, vcc
	v_cndmask_b32_e64 v110, v217, v110, s[98:99]
	v_cndmask_b32_e64 v111, v217, v111, s[96:97]
	v_cmp_le_i32_e64 vcc, 58, v16
	v_cmp_le_i32_e64 s[98:99], 59, v16
	s_nop 0
	v_cndmask_b32_e64 v112, v217, v112, vcc
	v_cndmask_b32_e64 v113, v217, v113, s[98:99]
	s_branch .LBB0_535

.Lmy_maskB:
	v_add_u32_e32 v2, s84, v222
	v_sub_u32_e32 v16, v184, v2
	v_subrev_u32_e32 v16, 0x780, v16
	v_cmp_le_i32_e64 vcc, 0, v16
	v_cmp_le_i32_e64 s[98:99], 1, v16
	v_cmp_le_i32_e64 s[96:97], 2, v16
	v_cndmask_b32_e64 v82, v217, v82, vcc
	v_cndmask_b32_e64 v83, v217, v83, s[98:99]
	v_cndmask_b32_e64 v84, v217, v84, s[96:97]
	v_cmp_le_i32_e64 vcc, 3, v16
	v_cmp_le_i32_e64 s[98:99], 8, v16
	v_cmp_le_i32_e64 s[96:97], 9, v16
	v_cndmask_b32_e64 v85, v217, v85, vcc
	v_cndmask_b32_e64 v86, v217, v86, s[98:99]
	v_cndmask_b32_e64 v87, v217, v87, s[96:97]
	v_cmp_le_i32_e64 vcc, 10, v16
	v_cmp_le_i32_e64 s[98:99], 11, v16
	v_cmp_le_i32_e64 s[96:97], 16, v16
	v_cndmask_b32_e64 v88, v217, v88, vcc
	v_cndmask_b32_e64 v89, v217, v89, s[98:99]
	v_cndmask_b32_e64 v90, v217, v90, s[96:97]
	v_cmp_le_i32_e64 vcc, 17, v16
	v_cmp_le_i32_e64 s[98:99], 18, v16
	v_cmp_le_i32_e64 s[96:97], 19, v16
	v_cndmask_b32_e64 v91, v217, v91, vcc
	v_cndmask_b32_e64 v92, v217, v92, s[98:99]
	v_cndmask_b32_e64 v93, v217, v93, s[96:97]
	v_cmp_le_i32_e64 vcc, 24, v16
	v_cmp_le_i32_e64 s[98:99], 25, v16
	v_cmp_le_i32_e64 s[96:97], 26, v16
	v_cndmask_b32_e64 v94, v217, v94, vcc
	v_cndmask_b32_e64 v95, v217, v95, s[98:99]
	v_cndmask_b32_e64 v96, v217, v96, s[96:97]
	v_cmp_le_i32_e64 vcc, 27, v16
	v_cmp_le_i32_e64 s[98:99], 32, v16
	v_cmp_le_i32_e64 s[96:97], 33, v16
	v_cndmask_b32_e64 v97, v217, v97, vcc
	v_cndmask_b32_e64 v98, v217, v98, s[98:99]
	v_cndmask_b32_e64 v99, v217, v99, s[96:97]
	v_cmp_le_i32_e64 vcc, 34, v16
	v_cmp_le_i32_e64 s[98:99], 35, v16
	v_cmp_le_i32_e64 s[96:97], 40, v16
	v_cndmask_b32_e64 v100, v217, v100, vcc
	v_cndmask_b32_e64 v101, v217, v101, s[98:99]
	v_cndmask_b32_e64 v102, v217, v102, s[96:97]
	v_cmp_le_i32_e64 vcc, 41, v16
	v_cmp_le_i32_e64 s[98:99], 42, v16
	v_cmp_le_i32_e64 s[96:97], 43, v16
	v_cndmask_b32_e64 v103, v217, v103, vcc
	v_cndmask_b32_e64 v104, v217, v104, s[98:99]
	v_cndmask_b32_e64 v105, v217, v105, s[96:97]
	v_cmp_le_i32_e64 vcc, 48, v16
	v_cmp_le_i32_e64 s[98:99], 49, v16
	v_cmp_le_i32_e64 s[96:97], 50, v16
	v_cndmask_b32_e64 v106, v217, v106, vcc
	v_cndmask_b32_e64 v107, v217, v107, s[98:99]
	v_cndmask_b32_e64 v108, v217, v108, s[96:97]
	v_cmp_le_i32_e64 vcc, 51, v16
	v_cmp_le_i32_e64 s[98:99], 56, v16
	v_cmp_le_i32_e64 s[96:97], 57, v16
	v_cndmask_b32_e64 v109, v217, v109, vcc
	v_cndmask_b32_e64 v110, v217, v110, s[98:99]
	v_cndmask_b32_e64 v111, v217, v111, s[96:97]
	v_cmp_le_i32_e64 vcc, 58, v16
	v_cmp_le_i32_e64 s[98:99], 59, v16
	s_nop 0
	v_cndmask_b32_e64 v112, v217, v112, vcc
	v_cndmask_b32_e64 v113, v217, v113, s[98:99]
	s_branch .LBB0_551
